# phase 0: modulation-vector weight loads and X copy batched (were one load per wait); final_g loaded once before the row loop
# speedup vs baseline: 1.0855x; 1.0091x over previous
; DI void phase0(const Params& p, unsigned char* smem) {
;     ...
;     } else if (it < B10) {
;       const int r0 = (it - B9) * 8;
;       f32x4* X = (f32x4*)(WS_ + O_X);
;       for (int e = tid; e < 8 * 512; e += 256) {
;         const int row = r0 + (e >> 9), cc = e & 511, b = row / SP, s = row - b * SP;
;         const f32x4* src = s < CTX ? (const f32x4*)(p.ctx + ((size_t)b * CTX + s) * DM) : (const f32x4*)(p.x + ((size_t)b * SEQ + s - CTX) * DM);
;         X[(size_t)row * 512 + cc] = src[cc];
;       }
.LBB0_16:
	s_or_b64 exec, exec, s[42:43]
	v_and_b32_e32 v3, 0x1ff, v10
	v_lshlrev_b32_e32 v50, 4, v3
	v_lshl_add_u64 v[4:5], v[8:9], 0, v[50:51]
	v_ashrrev_i32_e32 v3, 31, v2
	v_lshlrev_b64 v[2:3], 13, v[2:3]
	v_lshl_add_u64 v[2:3], s[48:49], 0, v[2:3]
	v_lshl_add_u64 v[2:3], v[2:3], 0, v[50:51]
	global_load_dwordx4 v[150:153], v[4:5], off
	s_mov_b64 s[34:35], 0x1000
	v_lshl_add_u64 v[146:147], v[4:5], 0, s[34:35]
	global_load_dwordx4 v[154:157], v[146:147], off
	s_mov_b64 s[34:35], 0x2000
	v_lshl_add_u64 v[146:147], v[4:5], 0, s[34:35]
	global_load_dwordx4 v[158:161], v[146:147], off
	s_mov_b64 s[34:35], 0x3000
	v_lshl_add_u64 v[146:147], v[4:5], 0, s[34:35]
	global_load_dwordx4 v[162:165], v[146:147], off
	s_mov_b64 s[34:35], 0x4000
	v_lshl_add_u64 v[146:147], v[4:5], 0, s[34:35]
	global_load_dwordx4 v[166:169], v[146:147], off
	s_mov_b64 s[34:35], 0x5000
	v_lshl_add_u64 v[146:147], v[4:5], 0, s[34:35]
	global_load_dwordx4 v[170:173], v[146:147], off
	s_mov_b64 s[34:35], 0x6000
	v_lshl_add_u64 v[146:147], v[4:5], 0, s[34:35]
	global_load_dwordx4 v[174:177], v[146:147], off
	s_mov_b64 s[34:35], 0x7000
	v_lshl_add_u64 v[146:147], v[4:5], 0, s[34:35]
	global_load_dwordx4 v[178:181], v[146:147], off
	s_mov_b64 s[34:35], 0x8000
	v_lshl_add_u64 v[146:147], v[4:5], 0, s[34:35]
	global_load_dwordx4 v[182:185], v[146:147], off
	s_mov_b64 s[34:35], 0x9000
	v_lshl_add_u64 v[146:147], v[4:5], 0, s[34:35]
	global_load_dwordx4 v[186:189], v[146:147], off
	s_mov_b64 s[34:35], 0xa000
	v_lshl_add_u64 v[146:147], v[4:5], 0, s[34:35]
	global_load_dwordx4 v[190:193], v[146:147], off
	s_mov_b64 s[34:35], 0xb000
	v_lshl_add_u64 v[146:147], v[4:5], 0, s[34:35]
	global_load_dwordx4 v[194:197], v[146:147], off
	s_mov_b64 s[34:35], 0xc000
	v_lshl_add_u64 v[146:147], v[4:5], 0, s[34:35]
	global_load_dwordx4 v[198:201], v[146:147], off
	s_mov_b64 s[34:35], 0xd000
	v_lshl_add_u64 v[146:147], v[4:5], 0, s[34:35]
	global_load_dwordx4 v[202:205], v[146:147], off
	s_mov_b64 s[34:35], 0xe000
	v_lshl_add_u64 v[146:147], v[4:5], 0, s[34:35]
	global_load_dwordx4 v[206:209], v[146:147], off
	s_mov_b64 s[34:35], 0xf000
	v_lshl_add_u64 v[146:147], v[4:5], 0, s[34:35]
	global_load_dwordx4 v[210:213], v[146:147], off
	s_waitcnt vmcnt(0)
	global_store_dwordx4 v[2:3], v[150:153], off
	s_mov_b64 s[34:35], 0x1000
	v_lshl_add_u64 v[146:147], v[2:3], 0, s[34:35]
	global_store_dwordx4 v[146:147], v[154:157], off
	s_mov_b64 s[34:35], 0x2000
	v_lshl_add_u64 v[146:147], v[2:3], 0, s[34:35]
	global_store_dwordx4 v[146:147], v[158:161], off
	s_mov_b64 s[34:35], 0x3000
	v_lshl_add_u64 v[146:147], v[2:3], 0, s[34:35]
	global_store_dwordx4 v[146:147], v[162:165], off
	s_mov_b64 s[34:35], 0x4000
	v_lshl_add_u64 v[146:147], v[2:3], 0, s[34:35]
	global_store_dwordx4 v[146:147], v[166:169], off
	s_mov_b64 s[34:35], 0x5000
	v_lshl_add_u64 v[146:147], v[2:3], 0, s[34:35]
	global_store_dwordx4 v[146:147], v[170:173], off
	s_mov_b64 s[34:35], 0x6000
	v_lshl_add_u64 v[146:147], v[2:3], 0, s[34:35]
	global_store_dwordx4 v[146:147], v[174:177], off
	s_mov_b64 s[34:35], 0x7000
	v_lshl_add_u64 v[146:147], v[2:3], 0, s[34:35]
	global_store_dwordx4 v[146:147], v[178:181], off
	s_mov_b64 s[34:35], 0x8000
	v_lshl_add_u64 v[146:147], v[2:3], 0, s[34:35]
	global_store_dwordx4 v[146:147], v[182:185], off
	s_mov_b64 s[34:35], 0x9000
	v_lshl_add_u64 v[146:147], v[2:3], 0, s[34:35]
	global_store_dwordx4 v[146:147], v[186:189], off
	s_mov_b64 s[34:35], 0xa000
	v_lshl_add_u64 v[146:147], v[2:3], 0, s[34:35]
	global_store_dwordx4 v[146:147], v[190:193], off
	s_mov_b64 s[34:35], 0xb000
	v_lshl_add_u64 v[146:147], v[2:3], 0, s[34:35]
	global_store_dwordx4 v[146:147], v[194:197], off
	s_mov_b64 s[34:35], 0xc000
	v_lshl_add_u64 v[146:147], v[2:3], 0, s[34:35]
	global_store_dwordx4 v[146:147], v[198:201], off
	s_mov_b64 s[34:35], 0xd000
	v_lshl_add_u64 v[146:147], v[2:3], 0, s[34:35]
	global_store_dwordx4 v[146:147], v[202:205], off
	s_mov_b64 s[34:35], 0xe000
	v_lshl_add_u64 v[146:147], v[2:3], 0, s[34:35]
	global_store_dwordx4 v[146:147], v[206:209], off
	s_mov_b64 s[34:35], 0xf000
	v_lshl_add_u64 v[146:147], v[2:3], 0, s[34:35]
	global_store_dwordx4 v[146:147], v[210:213], off
	s_branch .LBB0_21

; DI void phase0(const Params& p, unsigned char* smem) {
;     ...
;       const int l = it / 96, j = (it % 96) * 64 + lane, kq = wv;
;       const float* w = p.w_ada + (size_t)l * 2048 * 6144 + j;
;       float a0 = 0.f, a1 = 0.f, a2 = 0.f, a3 = 0.f, a4 = 0.f;
; #pragma unroll 32
;       for (int k = kq * 512; k < kq * 512 + 512; ++k) {
;         const float wv_ = w[(size_t)k * 6144];
;         a0 += sF[k] * wv_; a1 += sF[2048 + k] * wv_; a2 += sF[4096 + k] * wv_; a3 += sF[6144 + k] * wv_; a4 += sF[8192 + k] * wv_;
;       }
.LBB0_121:
	v_lshl_add_u64 v[18:19], v[16:17], 0, s[38:39]
	global_load_dword v150, v[18:19], off
	v_add_co_u32_e32 v146, vcc, 0x6000, v18
	s_nop 1
	v_addc_co_u32_e32 v147, vcc, 0, v19, vcc
	global_load_dword v151, v[146:147], off
	v_add_co_u32_e32 v148, vcc, 0xc000, v18
	s_nop 1
	v_addc_co_u32_e32 v149, vcc, 0, v19, vcc
	global_load_dword v152, v[148:149], off
	v_add_co_u32_e32 v146, vcc, 0x12000, v18
	s_nop 1
	v_addc_co_u32_e32 v147, vcc, 0, v19, vcc
	global_load_dword v153, v[146:147], off
	v_add_co_u32_e32 v148, vcc, 0x18000, v18
	s_nop 1
	v_addc_co_u32_e32 v149, vcc, 0, v19, vcc
	global_load_dword v154, v[148:149], off
	v_add_co_u32_e32 v146, vcc, 0x1e000, v18
	s_nop 1
	v_addc_co_u32_e32 v147, vcc, 0, v19, vcc
	global_load_dword v155, v[146:147], off
	v_add_co_u32_e32 v148, vcc, 0x24000, v18
	s_nop 1
	v_addc_co_u32_e32 v149, vcc, 0, v19, vcc
	global_load_dword v156, v[148:149], off
	v_add_co_u32_e32 v146, vcc, 0x2a000, v18
	s_nop 1
	v_addc_co_u32_e32 v147, vcc, 0, v19, vcc
	global_load_dword v157, v[146:147], off
	v_add_co_u32_e32 v148, vcc, 0x30000, v18
	s_nop 1
	v_addc_co_u32_e32 v149, vcc, 0, v19, vcc
	global_load_dword v158, v[148:149], off
	v_add_co_u32_e32 v146, vcc, 0x36000, v18
	s_nop 1
	v_addc_co_u32_e32 v147, vcc, 0, v19, vcc
	global_load_dword v159, v[146:147], off
	v_add_co_u32_e32 v148, vcc, 0x3c000, v18
	s_nop 1
	v_addc_co_u32_e32 v149, vcc, 0, v19, vcc
	global_load_dword v160, v[148:149], off
	v_add_co_u32_e32 v146, vcc, 0x42000, v18
	s_nop 1
	v_addc_co_u32_e32 v147, vcc, 0, v19, vcc
	global_load_dword v161, v[146:147], off
	v_add_co_u32_e32 v148, vcc, 0x48000, v18
	s_nop 1
	v_addc_co_u32_e32 v149, vcc, 0, v19, vcc
	global_load_dword v162, v[148:149], off
	v_add_co_u32_e32 v146, vcc, 0x4e000, v18
	s_nop 1
	v_addc_co_u32_e32 v147, vcc, 0, v19, vcc
	global_load_dword v163, v[146:147], off
	v_add_co_u32_e32 v148, vcc, 0x54000, v18
	s_nop 1
	v_addc_co_u32_e32 v149, vcc, 0, v19, vcc
	global_load_dword v164, v[148:149], off
	v_add_co_u32_e32 v146, vcc, 0x5a000, v18
	s_nop 1
	v_addc_co_u32_e32 v147, vcc, 0, v19, vcc
	global_load_dword v165, v[146:147], off
	v_add_co_u32_e32 v148, vcc, 0x60000, v18
	s_nop 1
	v_addc_co_u32_e32 v149, vcc, 0, v19, vcc
	global_load_dword v166, v[148:149], off
	v_add_co_u32_e32 v146, vcc, 0x66000, v18
	s_nop 1
	v_addc_co_u32_e32 v147, vcc, 0, v19, vcc
	global_load_dword v167, v[146:147], off
	v_add_co_u32_e32 v148, vcc, 0x6c000, v18
	s_nop 1
	v_addc_co_u32_e32 v149, vcc, 0, v19, vcc
	global_load_dword v168, v[148:149], off
	v_add_co_u32_e32 v146, vcc, 0x72000, v18
	s_nop 1
	v_addc_co_u32_e32 v147, vcc, 0, v19, vcc
	global_load_dword v169, v[146:147], off
	v_add_co_u32_e32 v148, vcc, 0x78000, v18
	s_nop 1
	v_addc_co_u32_e32 v149, vcc, 0, v19, vcc
	global_load_dword v170, v[148:149], off
	v_add_co_u32_e32 v146, vcc, 0x7e000, v18
	s_nop 1
	v_addc_co_u32_e32 v147, vcc, 0, v19, vcc
	global_load_dword v171, v[146:147], off
	v_add_co_u32_e32 v148, vcc, 0x84000, v18
	s_nop 1
	v_addc_co_u32_e32 v149, vcc, 0, v19, vcc
	global_load_dword v172, v[148:149], off
	v_add_co_u32_e32 v146, vcc, 0x8a000, v18
	s_nop 1
	v_addc_co_u32_e32 v147, vcc, 0, v19, vcc
	global_load_dword v173, v[146:147], off
	v_add_co_u32_e32 v148, vcc, 0x90000, v18
	s_nop 1
	v_addc_co_u32_e32 v149, vcc, 0, v19, vcc
	global_load_dword v174, v[148:149], off
	v_add_co_u32_e32 v146, vcc, 0x96000, v18
	s_nop 1
	v_addc_co_u32_e32 v147, vcc, 0, v19, vcc
	global_load_dword v175, v[146:147], off
	v_add_co_u32_e32 v148, vcc, 0x9c000, v18
	s_nop 1
	v_addc_co_u32_e32 v149, vcc, 0, v19, vcc
	global_load_dword v176, v[148:149], off
	v_add_co_u32_e32 v146, vcc, 0xa2000, v18
	s_nop 1
	v_addc_co_u32_e32 v147, vcc, 0, v19, vcc
	global_load_dword v177, v[146:147], off
	v_add_co_u32_e32 v148, vcc, 0xa8000, v18
	s_nop 1
	v_addc_co_u32_e32 v149, vcc, 0, v19, vcc
	global_load_dword v178, v[148:149], off
	v_add_co_u32_e32 v146, vcc, 0xae000, v18
	s_nop 1
	v_addc_co_u32_e32 v147, vcc, 0, v19, vcc
	global_load_dword v179, v[146:147], off
	v_add_co_u32_e32 v148, vcc, 0xb4000, v18
	s_nop 1
	v_addc_co_u32_e32 v149, vcc, 0, v19, vcc
	global_load_dword v180, v[148:149], off
	v_add_co_u32_e32 v146, vcc, 0xba000, v18
	s_nop 1
	v_addc_co_u32_e32 v147, vcc, 0, v19, vcc
	global_load_dword v181, v[146:147], off
	s_waitcnt vmcnt(0)
	v_mov_b32_e32 v50, v150
	ds_read_b128 v[26:29], v25
	ds_read_b128 v[10:13], v25 offset:16
	ds_read_b128 v[6:9], v25 offset:32
	ds_read_b128 v[2:5], v25 offset:48
	ds_read_b128 v[30:33], v25 offset:8192
	s_waitcnt lgkmcnt(0)
	v_mov_b32_e32 v108, v26
	v_add_co_u32_e32 v120, vcc, s81, v18
	s_mov_b32 s34, 0x84000
	v_mov_b32_e32 v109, v30
	v_addc_co_u32_e32 v121, vcc, 0, v19, vcc
	v_mov_b32_e32 v30, v27
	s_add_u32 s38, s38, 0xc0000
	s_addc_u32 s39, s39, 0
	s_cmp_eq_u32 s38, 0xc00000
	s_waitcnt vmcnt(0)
	v_pk_fma_f32 v[116:117], v[50:51], v[108:109], v[22:23] op_sel_hi:[0,1,1]
	ds_read_b128 v[108:111], v25 offset:16384
	ds_read_b128 v[112:115], v25 offset:24576
	s_waitcnt lgkmcnt(1)
	v_mov_b32_e32 v22, v108
	s_waitcnt lgkmcnt(0)
	v_mov_b32_e32 v23, v112
	v_pk_fma_f32 v[118:119], v[50:51], v[22:23], v[20:21] op_sel_hi:[0,1,1]
	ds_read_b128 v[20:23], v25 offset:32768
	v_mov_b32_e32 v112, v109
	v_mov_b32_e32 v108, v28
	v_mov_b32_e32 v109, v32
	v_mov_b32_e32 v32, v29
	s_waitcnt lgkmcnt(0)
	v_fmac_f32_e32 v24, v50, v20
	s_waitcnt vmcnt(0)
	v_mov_b32_e32 v20, v151
	v_mov_b32_e32 v28, v10
	s_waitcnt vmcnt(0)
	v_pk_fma_f32 v[26:27], v[20:21], v[30:31], v[116:117] op_sel_hi:[0,1,1]
	v_pk_fma_f32 v[30:31], v[20:21], v[112:113], v[118:119] op_sel_hi:[0,1,1]
	v_fmac_f32_e32 v24, v20, v21
	v_add_co_u32_e32 v20, vcc, s94, v18
	s_nop 1
	v_addc_co_u32_e32 v21, vcc, 0, v19, vcc
	s_waitcnt vmcnt(0)
; DI void phase0(const Params& p, unsigned char* smem) {
;     ...
;       for (int k = kq * 512; k < kq * 512 + 512; ++k) {
;         const float wv_ = w[(size_t)k * 6144];
;         a0 += sF[k] * wv_; a1 += sF[2048 + k] * wv_; a2 += sF[4096 + k] * wv_; a3 += sF[6144 + k] * wv_; a4 += sF[8192 + k] * wv_;
;       }
	v_mov_b32_e32 v20, v152
	s_waitcnt vmcnt(0)
	v_pk_fma_f32 v[26:27], v[20:21], v[108:109], v[26:27] op_sel_hi:[0,1,1]
	v_mov_b32_e32 v108, v110
	v_mov_b32_e32 v109, v114
	v_pk_fma_f32 v[30:31], v[20:21], v[108:109], v[30:31] op_sel_hi:[0,1,1]
	v_fmac_f32_e32 v24, v20, v22
	v_add_co_u32_e32 v20, vcc, s83, v18
	v_mov_b32_e32 v114, v111
	s_nop 0
	v_addc_co_u32_e32 v21, vcc, 0, v19, vcc
	s_waitcnt vmcnt(0)
	v_mov_b32_e32 v20, v153
	s_waitcnt vmcnt(0)
	v_pk_fma_f32 v[26:27], v[20:21], v[32:33], v[26:27] op_sel_hi:[0,1,1]
	v_pk_fma_f32 v[108:109], v[20:21], v[114:115], v[30:31] op_sel_hi:[0,1,1]
	v_fmac_f32_e32 v24, v20, v23
	v_add_co_u32_e32 v20, vcc, s84, v18
	s_nop 1
	v_addc_co_u32_e32 v21, vcc, 0, v19, vcc
	s_waitcnt vmcnt(0)
	v_mov_b32_e32 v50, v154
	ds_read_b128 v[20:23], v25 offset:8208
	v_add_co_u32_e32 v116, vcc, s85, v18
	s_waitcnt lgkmcnt(0)
	v_mov_b32_e32 v29, v20
	v_addc_co_u32_e32 v117, vcc, 0, v19, vcc
	v_mov_b32_e32 v20, v11
	s_waitcnt vmcnt(0)
	v_pk_fma_f32 v[112:113], v[50:51], v[28:29], v[26:27] op_sel_hi:[0,1,1]
	ds_read_b128 v[26:29], v25 offset:16400
	ds_read_b128 v[30:33], v25 offset:24592
	s_waitcnt vmcnt(0)
	v_mov_b32_e32 v10, v155
	s_waitcnt lgkmcnt(1)
	v_mov_b32_e32 v110, v26
	s_waitcnt lgkmcnt(0)
	v_mov_b32_e32 v111, v30
	v_pk_fma_f32 v[114:115], v[50:51], v[110:111], v[108:109] op_sel_hi:[0,1,1]
	ds_read_b128 v[108:111], v25 offset:32784
	v_mov_b32_e32 v30, v27
	s_waitcnt lgkmcnt(0)
	v_fmac_f32_e32 v24, v50, v108
	s_waitcnt vmcnt(0)
	v_pk_fma_f32 v[20:21], v[10:11], v[20:21], v[112:113] op_sel_hi:[0,1,1]
	v_pk_fma_f32 v[26:27], v[10:11], v[30:31], v[114:115] op_sel_hi:[0,1,1]
	v_fmac_f32_e32 v24, v10, v109
	v_add_co_u32_e32 v10, vcc, s87, v18
	v_mov_b32_e32 v30, v12
	s_nop 0
	v_addc_co_u32_e32 v11, vcc, 0, v19, vcc
	s_waitcnt vmcnt(0)
	v_mov_b32_e32 v10, v156
	v_mov_b32_e32 v31, v22
	v_mov_b32_e32 v22, v13
	s_waitcnt vmcnt(0)
	v_pk_fma_f32 v[20:21], v[10:11], v[30:31], v[20:21] op_sel_hi:[0,1,1]
	v_mov_b32_e32 v30, v28
	v_mov_b32_e32 v31, v32
	v_pk_fma_f32 v[26:27], v[10:11], v[30:31], v[26:27] op_sel_hi:[0,1,1]
	v_fmac_f32_e32 v24, v10, v110
	v_add_co_u32_e32 v10, vcc, s89, v18
	v_mov_b32_e32 v32, v29
	s_nop 0
	v_addc_co_u32_e32 v11, vcc, 0, v19, vcc
	s_waitcnt vmcnt(0)
	v_mov_b32_e32 v10, v157
	s_waitcnt vmcnt(0)
	v_pk_fma_f32 v[20:21], v[10:11], v[22:23], v[20:21] op_sel_hi:[0,1,1]
	v_pk_fma_f32 v[30:31], v[10:11], v[32:33], v[26:27] op_sel_hi:[0,1,1]
	v_fmac_f32_e32 v24, v10, v111
	v_add_co_u32_e32 v10, vcc, s90, v18
	v_mov_b32_e32 v22, v6
	s_nop 0
	v_addc_co_u32_e32 v11, vcc, 0, v19, vcc
	s_waitcnt vmcnt(0)
	v_mov_b32_e32 v50, v158
	ds_read_b128 v[10:13], v25 offset:8224
	v_add_co_u32_e32 v112, vcc, s91, v18
	s_waitcnt lgkmcnt(0)
	v_mov_b32_e32 v23, v10
	v_addc_co_u32_e32 v113, vcc, 0, v19, vcc
	v_mov_b32_e32 v10, v7
	s_waitcnt vmcnt(0)
	v_pk_fma_f32 v[108:109], v[50:51], v[22:23], v[20:21] op_sel_hi:[0,1,1]
	ds_read_b128 v[20:23], v25 offset:16416
	ds_read_b128 v[26:29], v25 offset:24608
	s_waitcnt vmcnt(0)
	v_mov_b32_e32 v6, v159
	s_waitcnt lgkmcnt(1)
	v_mov_b32_e32 v32, v20
	s_waitcnt lgkmcnt(0)
	v_mov_b32_e32 v33, v26
	v_pk_fma_f32 v[110:111], v[50:51], v[32:33], v[30:31] op_sel_hi:[0,1,1]
	ds_read_b128 v[30:33], v25 offset:32800
	v_mov_b32_e32 v26, v21
	s_waitcnt lgkmcnt(0)
	v_fmac_f32_e32 v24, v50, v30
	s_waitcnt vmcnt(0)
	v_pk_fma_f32 v[10:11], v[6:7], v[10:11], v[108:109] op_sel_hi:[0,1,1]
	v_pk_fma_f32 v[20:21], v[6:7], v[26:27], v[110:111] op_sel_hi:[0,1,1]
	v_fmac_f32_e32 v24, v6, v31
	v_add_co_u32_e32 v6, vcc, s37, v18
	v_mov_b32_e32 v26, v8
	s_nop 0
	v_addc_co_u32_e32 v7, vcc, 0, v19, vcc
	s_waitcnt vmcnt(0)
	v_mov_b32_e32 v6, v160
	v_mov_b32_e32 v27, v12
	v_mov_b32_e32 v12, v9
	s_waitcnt vmcnt(0)
	v_pk_fma_f32 v[10:11], v[6:7], v[26:27], v[10:11] op_sel_hi:[0,1,1]
	v_mov_b32_e32 v26, v22
	v_mov_b32_e32 v27, v28
	v_pk_fma_f32 v[20:21], v[6:7], v[26:27], v[20:21] op_sel_hi:[0,1,1]
	v_fmac_f32_e32 v24, v6, v32
	v_add_co_u32_e32 v6, vcc, s5, v18
	v_mov_b32_e32 v28, v23
	s_nop 0
	v_addc_co_u32_e32 v7, vcc, 0, v19, vcc
	s_waitcnt vmcnt(0)
	v_mov_b32_e32 v6, v161
	s_waitcnt vmcnt(0)
	v_pk_fma_f32 v[10:11], v[6:7], v[12:13], v[10:11] op_sel_hi:[0,1,1]
	v_pk_fma_f32 v[26:27], v[6:7], v[28:29], v[20:21] op_sel_hi:[0,1,1]
	v_fmac_f32_e32 v24, v6, v33
	v_add_co_u32_e32 v6, vcc, s6, v18
	v_mov_b32_e32 v12, v2
	s_nop 0
	v_addc_co_u32_e32 v7, vcc, 0, v19, vcc
	s_waitcnt vmcnt(0)
	v_mov_b32_e32 v30, v162
	ds_read_b128 v[6:9], v25 offset:8240
	s_waitcnt lgkmcnt(0)
	v_mov_b32_e32 v13, v6
	v_mov_b32_e32 v6, v3
	s_waitcnt vmcnt(0)
	v_pk_fma_f32 v[32:33], v[30:31], v[12:13], v[10:11] op_sel_hi:[0,1,1]
	ds_read_b128 v[10:13], v25 offset:16432
	ds_read_b128 v[20:23], v25 offset:24624
	s_waitcnt lgkmcnt(1)
	v_mov_b32_e32 v28, v10
	s_waitcnt lgkmcnt(0)
	v_mov_b32_e32 v29, v20
	v_pk_fma_f32 v[108:109], v[30:31], v[28:29], v[26:27] op_sel_hi:[0,1,1]
	ds_read_b128 v[26:29], v25 offset:32816
	v_mov_b32_e32 v20, v11
	s_waitcnt lgkmcnt(0)
	v_fmac_f32_e32 v24, v30, v26
	v_add_co_u32_e32 v30, vcc, s7, v18
	s_nop 1
	v_addc_co_u32_e32 v31, vcc, 0, v19, vcc
	s_waitcnt vmcnt(0)
	v_mov_b32_e32 v2, v163
	s_waitcnt vmcnt(0)
	v_pk_fma_f32 v[6:7], v[2:3], v[6:7], v[32:33] op_sel_hi:[0,1,1]
	v_pk_fma_f32 v[10:11], v[2:3], v[20:21], v[108:109] op_sel_hi:[0,1,1]
	v_fmac_f32_e32 v24, v2, v27
	v_add_co_u32_e32 v2, vcc, s9, v18
	v_mov_b32_e32 v20, v4
	s_nop 0
	v_addc_co_u32_e32 v3, vcc, 0, v19, vcc
	s_waitcnt vmcnt(0)
	v_mov_b32_e32 v2, v164
	v_mov_b32_e32 v21, v8
	v_mov_b32_e32 v8, v5
	s_waitcnt vmcnt(0)
; DI void phase0(const Params& p, unsigned char* smem) {
;     ...
;       for (int k = kq * 512; k < kq * 512 + 512; ++k) {
;         const float wv_ = w[(size_t)k * 6144];
;         a0 += sF[k] * wv_; a1 += sF[2048 + k] * wv_; a2 += sF[4096 + k] * wv_; a3 += sF[6144 + k] * wv_; a4 += sF[8192 + k] * wv_;
;       }
	v_pk_fma_f32 v[6:7], v[2:3], v[20:21], v[6:7] op_sel_hi:[0,1,1]
	v_mov_b32_e32 v20, v12
	v_mov_b32_e32 v21, v22
	v_pk_fma_f32 v[10:11], v[2:3], v[20:21], v[10:11] op_sel_hi:[0,1,1]
	v_fmac_f32_e32 v24, v2, v28
	v_add_co_u32_e32 v2, vcc, s25, v18
	v_mov_b32_e32 v22, v13
	s_nop 0
	v_addc_co_u32_e32 v3, vcc, 0, v19, vcc
	s_waitcnt vmcnt(0)
	v_mov_b32_e32 v2, v165
	s_waitcnt vmcnt(0)
	v_pk_fma_f32 v[20:21], v[2:3], v[8:9], v[6:7] op_sel_hi:[0,1,1]
	v_pk_fma_f32 v[26:27], v[2:3], v[22:23], v[10:11] op_sel_hi:[0,1,1]
	v_fmac_f32_e32 v24, v2, v29
	v_add_co_u32_e32 v2, vcc, s22, v18
	s_nop 1
	v_addc_co_u32_e32 v3, vcc, 0, v19, vcc
	s_waitcnt vmcnt(0)
	v_mov_b32_e32 v30, v166
	ds_read_b128 v[2:5], v25 offset:64
	ds_read_b128 v[6:9], v25 offset:8256
	s_waitcnt lgkmcnt(1)
	v_mov_b32_e32 v10, v2
	s_waitcnt lgkmcnt(0)
	v_mov_b32_e32 v11, v6
	v_mov_b32_e32 v6, v3
	s_waitcnt vmcnt(0)
	v_pk_fma_f32 v[32:33], v[30:31], v[10:11], v[20:21] op_sel_hi:[0,1,1]
	ds_read_b128 v[10:13], v25 offset:16448
	ds_read_b128 v[20:23], v25 offset:24640
	s_waitcnt lgkmcnt(1)
	v_mov_b32_e32 v28, v10
	s_waitcnt lgkmcnt(0)
	v_mov_b32_e32 v29, v20
	v_pk_fma_f32 v[108:109], v[30:31], v[28:29], v[26:27] op_sel_hi:[0,1,1]
	ds_read_b128 v[26:29], v25 offset:32832
	v_mov_b32_e32 v20, v11
	s_waitcnt lgkmcnt(0)
	v_fmac_f32_e32 v24, v30, v26
	v_add_co_u32_e32 v30, vcc, s23, v18
	s_nop 1
	v_addc_co_u32_e32 v31, vcc, 0, v19, vcc
	s_waitcnt vmcnt(0)
	v_mov_b32_e32 v2, v167
	s_waitcnt vmcnt(0)
	v_pk_fma_f32 v[6:7], v[2:3], v[6:7], v[32:33] op_sel_hi:[0,1,1]
	v_pk_fma_f32 v[10:11], v[2:3], v[20:21], v[108:109] op_sel_hi:[0,1,1]
	v_fmac_f32_e32 v24, v2, v27
	v_add_co_u32_e32 v2, vcc, s10, v18
	v_mov_b32_e32 v20, v4
	s_nop 0
	v_addc_co_u32_e32 v3, vcc, 0, v19, vcc
	s_waitcnt vmcnt(0)
	v_mov_b32_e32 v2, v168
	v_mov_b32_e32 v21, v8
	v_mov_b32_e32 v8, v5
	s_waitcnt vmcnt(0)
	v_pk_fma_f32 v[6:7], v[2:3], v[20:21], v[6:7] op_sel_hi:[0,1,1]
	v_mov_b32_e32 v20, v12
	v_mov_b32_e32 v21, v22
	v_pk_fma_f32 v[10:11], v[2:3], v[20:21], v[10:11] op_sel_hi:[0,1,1]
	v_fmac_f32_e32 v24, v2, v28
	v_add_co_u32_e32 v2, vcc, s28, v18
	v_mov_b32_e32 v22, v13
	s_nop 0
	v_addc_co_u32_e32 v3, vcc, 0, v19, vcc
	s_waitcnt vmcnt(0)
	v_mov_b32_e32 v2, v169
	s_waitcnt vmcnt(0)
	v_pk_fma_f32 v[20:21], v[2:3], v[8:9], v[6:7] op_sel_hi:[0,1,1]
	v_pk_fma_f32 v[26:27], v[2:3], v[22:23], v[10:11] op_sel_hi:[0,1,1]
	v_fmac_f32_e32 v24, v2, v29
	v_add_co_u32_e32 v2, vcc, s29, v18
	s_nop 1
	v_addc_co_u32_e32 v3, vcc, 0, v19, vcc
	s_waitcnt vmcnt(0)
	v_mov_b32_e32 v30, v170
	ds_read_b128 v[2:5], v25 offset:80
	ds_read_b128 v[6:9], v25 offset:8272
	s_waitcnt lgkmcnt(1)
	v_mov_b32_e32 v10, v2
	s_waitcnt lgkmcnt(0)
	v_mov_b32_e32 v11, v6
	v_mov_b32_e32 v6, v3
	s_waitcnt vmcnt(0)
	v_pk_fma_f32 v[32:33], v[30:31], v[10:11], v[20:21] op_sel_hi:[0,1,1]
	ds_read_b128 v[10:13], v25 offset:16464
	ds_read_b128 v[20:23], v25 offset:24656
	s_waitcnt lgkmcnt(1)
	v_mov_b32_e32 v28, v10
	s_waitcnt lgkmcnt(0)
	v_mov_b32_e32 v29, v20
	v_pk_fma_f32 v[108:109], v[30:31], v[28:29], v[26:27] op_sel_hi:[0,1,1]
	ds_read_b128 v[26:29], v25 offset:32848
	v_mov_b32_e32 v20, v11
	s_waitcnt lgkmcnt(0)
	v_fmac_f32_e32 v24, v30, v26
	v_add_co_u32_e32 v30, vcc, s30, v18
	s_nop 1
	v_addc_co_u32_e32 v31, vcc, 0, v19, vcc
	s_waitcnt vmcnt(0)
	v_mov_b32_e32 v2, v171
	s_waitcnt vmcnt(0)
	v_pk_fma_f32 v[6:7], v[2:3], v[6:7], v[32:33] op_sel_hi:[0,1,1]
	v_pk_fma_f32 v[10:11], v[2:3], v[20:21], v[108:109] op_sel_hi:[0,1,1]
	v_fmac_f32_e32 v24, v2, v27
	v_add_co_u32_e32 v2, vcc, s34, v18
	v_mov_b32_e32 v20, v4
	s_nop 0
	v_addc_co_u32_e32 v3, vcc, 0, v19, vcc
	s_waitcnt vmcnt(0)
	v_mov_b32_e32 v2, v172
	v_mov_b32_e32 v21, v8
	s_mov_b32 s34, 0x8a000
	v_mov_b32_e32 v8, v5
	s_waitcnt vmcnt(0)
	v_pk_fma_f32 v[6:7], v[2:3], v[20:21], v[6:7] op_sel_hi:[0,1,1]
	v_mov_b32_e32 v20, v12
	v_mov_b32_e32 v21, v22
	v_pk_fma_f32 v[10:11], v[2:3], v[20:21], v[10:11] op_sel_hi:[0,1,1]
	v_fmac_f32_e32 v24, v2, v28
	v_add_co_u32_e32 v2, vcc, s34, v18
	v_mov_b32_e32 v22, v13
	s_nop 0
	v_addc_co_u32_e32 v3, vcc, 0, v19, vcc
	s_waitcnt vmcnt(0)
	v_mov_b32_e32 v2, v173
	s_mov_b32 s34, 0x96000
	s_waitcnt vmcnt(0)
	v_pk_fma_f32 v[20:21], v[2:3], v[8:9], v[6:7] op_sel_hi:[0,1,1]
	v_pk_fma_f32 v[26:27], v[2:3], v[22:23], v[10:11] op_sel_hi:[0,1,1]
	v_fmac_f32_e32 v24, v2, v29
	v_add_co_u32_e32 v2, vcc, s0, v18
	s_nop 1
	v_addc_co_u32_e32 v3, vcc, 0, v19, vcc
	s_waitcnt vmcnt(0)
	v_mov_b32_e32 v30, v174
	ds_read_b128 v[2:5], v25 offset:96
	ds_read_b128 v[6:9], v25 offset:8288
	s_waitcnt lgkmcnt(1)
	v_mov_b32_e32 v10, v2
	s_waitcnt lgkmcnt(0)
	v_mov_b32_e32 v11, v6
	v_mov_b32_e32 v6, v3
	s_waitcnt vmcnt(0)
	v_pk_fma_f32 v[32:33], v[30:31], v[10:11], v[20:21] op_sel_hi:[0,1,1]
	ds_read_b128 v[10:13], v25 offset:16480
	ds_read_b128 v[20:23], v25 offset:24672
	s_waitcnt lgkmcnt(1)
	v_mov_b32_e32 v28, v10
	s_waitcnt lgkmcnt(0)
	v_mov_b32_e32 v29, v20
	v_pk_fma_f32 v[108:109], v[30:31], v[28:29], v[26:27] op_sel_hi:[0,1,1]
	ds_read_b128 v[26:29], v25 offset:32864
	v_mov_b32_e32 v20, v11
	s_waitcnt lgkmcnt(0)
	v_fmac_f32_e32 v24, v30, v26
	v_add_co_u32_e32 v30, vcc, s34, v18
	s_mov_b32 s34, 0x9c000
	s_nop 0
	v_addc_co_u32_e32 v31, vcc, 0, v19, vcc
	s_waitcnt vmcnt(0)
	v_mov_b32_e32 v2, v175
	s_waitcnt vmcnt(0)
	v_pk_fma_f32 v[6:7], v[2:3], v[6:7], v[32:33] op_sel_hi:[0,1,1]
	v_pk_fma_f32 v[10:11], v[2:3], v[20:21], v[108:109] op_sel_hi:[0,1,1]
	v_fmac_f32_e32 v24, v2, v27
	v_add_co_u32_e32 v2, vcc, s34, v18
	v_mov_b32_e32 v20, v4
	s_nop 0
	v_addc_co_u32_e32 v3, vcc, 0, v19, vcc
	s_waitcnt vmcnt(0)
	v_mov_b32_e32 v2, v176
	v_mov_b32_e32 v21, v8
	s_mov_b32 s34, 0xa2000
	v_mov_b32_e32 v8, v5
	s_waitcnt vmcnt(0)
; DI void phase0(const Params& p, unsigned char* smem) {
;     ...
; #pragma unroll 32
;       for (int k = kq * 512; k < kq * 512 + 512; ++k) {
;         const float wv_ = w[(size_t)k * 6144];
;         a0 += sF[k] * wv_; a1 += sF[2048 + k] * wv_; a2 += sF[4096 + k] * wv_; a3 += sF[6144 + k] * wv_; a4 += sF[8192 + k] * wv_;
;       }
;       float* red = sF + 10240 + (kq * 5) * 64 + lane;
;       red[0] = a0; red[64] = a1; red[128] = a2; red[192] = a3; red[256] = a4;
;       __syncthreads();
;       if (wv == 0) {
;         const float bb = p.b_ada[l * 6144 + j];
;         float* M = (float*)(WS_ + O_MODS) + (size_t)l * 5 * 6144 + j;
;         for (int v = 0; v < 5; ++v) {
;           const float* r = sF + 10240 + v * 64 + lane;
;           M[(size_t)v * 6144] = r[0] + r[320] + r[640] + r[960] + bb;
;         }
	v_pk_fma_f32 v[6:7], v[2:3], v[20:21], v[6:7] op_sel_hi:[0,1,1]
	v_mov_b32_e32 v20, v12
	v_mov_b32_e32 v21, v22
	v_pk_fma_f32 v[10:11], v[2:3], v[20:21], v[10:11] op_sel_hi:[0,1,1]
	v_fmac_f32_e32 v24, v2, v28
	v_add_co_u32_e32 v2, vcc, s34, v18
	v_mov_b32_e32 v22, v13
	s_nop 0
	v_addc_co_u32_e32 v3, vcc, 0, v19, vcc
	s_waitcnt vmcnt(0)
	v_mov_b32_e32 v2, v177
	s_mov_b32 s34, 0xae000
	s_waitcnt vmcnt(0)
	v_pk_fma_f32 v[20:21], v[2:3], v[8:9], v[6:7] op_sel_hi:[0,1,1]
	v_pk_fma_f32 v[22:23], v[2:3], v[22:23], v[10:11] op_sel_hi:[0,1,1]
	v_fmac_f32_e32 v24, v2, v29
	v_add_co_u32_e32 v2, vcc, s13, v18
	s_nop 1
	v_addc_co_u32_e32 v3, vcc, 0, v19, vcc
	s_waitcnt vmcnt(0)
	v_mov_b32_e32 v50, v178
	ds_read_b128 v[2:5], v25 offset:112
	ds_read_b128 v[6:9], v25 offset:8304
	v_add_co_u32_e32 v108, vcc, s34, v18
	s_mov_b32 s34, 0xb4000
	s_waitcnt lgkmcnt(1)
	v_mov_b32_e32 v10, v2
	s_waitcnt lgkmcnt(0)
	v_mov_b32_e32 v11, v6
	v_addc_co_u32_e32 v109, vcc, 0, v19, vcc
	v_mov_b32_e32 v6, v3
	s_waitcnt vmcnt(0)
	v_pk_fma_f32 v[20:21], v[50:51], v[10:11], v[20:21] op_sel_hi:[0,1,1]
	ds_read_b128 v[10:13], v25 offset:16496
	ds_read_b128 v[26:29], v25 offset:24688
	s_waitcnt vmcnt(0)
	v_mov_b32_e32 v2, v179
	s_waitcnt lgkmcnt(1)
	v_mov_b32_e32 v30, v10
	s_waitcnt lgkmcnt(0)
	v_mov_b32_e32 v31, v26
	v_pk_fma_f32 v[22:23], v[50:51], v[30:31], v[22:23] op_sel_hi:[0,1,1]
	ds_read_b128 v[30:33], v25 offset:32880
	v_mov_b32_e32 v26, v11
	v_add_u32_e32 v25, 0x80, v25
	s_waitcnt lgkmcnt(0)
	v_fmac_f32_e32 v24, v50, v30
	s_waitcnt vmcnt(0)
	v_pk_fma_f32 v[6:7], v[2:3], v[6:7], v[20:21] op_sel_hi:[0,1,1]
	v_pk_fma_f32 v[10:11], v[2:3], v[26:27], v[22:23] op_sel_hi:[0,1,1]
	v_fmac_f32_e32 v24, v2, v31
	v_add_co_u32_e32 v2, vcc, s34, v18
	v_mov_b32_e32 v20, v4
	s_nop 0
	v_addc_co_u32_e32 v3, vcc, 0, v19, vcc
	s_waitcnt vmcnt(0)
	v_mov_b32_e32 v2, v180
	v_mov_b32_e32 v21, v8
	s_mov_b32 s34, 0xba000
	v_mov_b32_e32 v8, v5
	s_waitcnt vmcnt(0)
	v_pk_fma_f32 v[6:7], v[2:3], v[20:21], v[6:7] op_sel_hi:[0,1,1]
	v_mov_b32_e32 v20, v12
	v_mov_b32_e32 v21, v28
	v_pk_fma_f32 v[10:11], v[2:3], v[20:21], v[10:11] op_sel_hi:[0,1,1]
	v_fmac_f32_e32 v24, v2, v32
	v_add_co_u32_e32 v2, vcc, s34, v18
	v_mov_b32_e32 v28, v13
	s_nop 0
	v_addc_co_u32_e32 v3, vcc, 0, v19, vcc
	s_waitcnt vmcnt(0)
	v_mov_b32_e32 v2, v181
	s_waitcnt vmcnt(0)
	v_pk_fma_f32 v[22:23], v[2:3], v[8:9], v[6:7] op_sel_hi:[0,1,1]
	v_pk_fma_f32 v[20:21], v[2:3], v[28:29], v[10:11] op_sel_hi:[0,1,1]
	v_fmac_f32_e32 v24, v2, v33
	s_cbranch_scc0 .LBB0_121
	ds_write2st64_b32 v103, v22, v23 offset0:160 offset1:161
	ds_write2st64_b32 v103, v20, v21 offset0:162 offset1:163
	ds_write_b32 v103, v24 offset:41984
	s_waitcnt lgkmcnt(0)
	s_barrier
	s_and_saveexec_b64 s[38:39], s[20:21]
	s_cbranch_execz .LBB0_2
	s_mul_i32 s34, s40, 0x1800
	v_add_u32_e32 v2, s34, v14
	v_readlane_b32 s60, v254, 29
	v_ashrrev_i32_e32 v3, 31, v2
	v_readlane_b32 s72, v254, 41
	v_readlane_b32 s73, v254, 42
	s_mul_i32 s35, s40, 0x1e000
	s_mul_hi_i32 s34, s40, 0x1e000
	v_lshl_add_u64 v[2:3], v[2:3], 2, s[72:73]
	global_load_dword v6, v[2:3], off
	ds_read_b32 v4, v47 offset:40960
	ds_read_b32 v5, v47 offset:42240
	s_add_u32 s40, s76, s35
	s_addc_u32 s41, s77, s34
	v_lshl_add_u64 v[2:3], v[14:15], 2, s[40:41]
	v_readlane_b32 s61, v254, 30
	s_waitcnt lgkmcnt(0)
	v_add_f32_e32 v4, v4, v5
	ds_read_b32 v5, v47 offset:43520
	v_readlane_b32 s62, v254, 31
	v_readlane_b32 s63, v254, 32
	v_readlane_b32 s64, v254, 33
	v_readlane_b32 s65, v254, 34
	s_waitcnt lgkmcnt(0)
	v_add_f32_e32 v4, v4, v5
	ds_read_b32 v5, v47 offset:44800
	v_readlane_b32 s66, v254, 35
	v_readlane_b32 s67, v254, 36
	v_readlane_b32 s68, v254, 37
	v_readlane_b32 s69, v254, 38
	s_waitcnt lgkmcnt(0)
	v_add_f32_e32 v4, v4, v5
	v_readlane_b32 s70, v254, 39
	v_readlane_b32 s71, v254, 40
	v_readlane_b32 s74, v254, 43
	v_readlane_b32 s75, v254, 44
	s_waitcnt vmcnt(0)
	v_add_f32_e32 v4, v6, v4
	flat_store_dword v[2:3], v4
	ds_read_b32 v4, v47 offset:41216
	ds_read_b32 v5, v47 offset:42496
	s_waitcnt lgkmcnt(0)
	v_add_f32_e32 v4, v4, v5
	ds_read_b32 v5, v47 offset:43776
	s_waitcnt lgkmcnt(0)
	v_add_f32_e32 v4, v4, v5
	ds_read_b32 v5, v47 offset:45056
	s_waitcnt lgkmcnt(0)
	v_add_f32_e32 v4, v4, v5
	v_add_f32_e32 v7, v6, v4
	v_add_co_u32_e32 v4, vcc, s81, v2
	s_nop 1
	v_addc_co_u32_e32 v5, vcc, 0, v3, vcc
	flat_store_dword v[4:5], v7
	ds_read_b32 v4, v47 offset:41472
	ds_read_b32 v5, v47 offset:42752
	s_waitcnt lgkmcnt(0)
	v_add_f32_e32 v4, v4, v5
	ds_read_b32 v5, v47 offset:44032
	s_waitcnt lgkmcnt(0)
	v_add_f32_e32 v4, v4, v5
	ds_read_b32 v5, v47 offset:45312
	s_waitcnt lgkmcnt(0)
	v_add_f32_e32 v4, v4, v5
	v_add_f32_e32 v7, v6, v4
	v_add_co_u32_e32 v4, vcc, s94, v2
	s_nop 1
	v_addc_co_u32_e32 v5, vcc, 0, v3, vcc
	flat_store_dword v[4:5], v7
	ds_read_b32 v4, v47 offset:41728
	ds_read_b32 v5, v47 offset:43008
	s_waitcnt lgkmcnt(0)
	v_add_f32_e32 v4, v4, v5
	ds_read_b32 v5, v47 offset:44288
	s_waitcnt lgkmcnt(0)
	v_add_f32_e32 v4, v4, v5
	ds_read_b32 v5, v47 offset:45568
	s_waitcnt lgkmcnt(0)
	v_add_f32_e32 v4, v4, v5
	v_add_f32_e32 v7, v6, v4
	v_add_co_u32_e32 v4, vcc, s83, v2
	s_nop 1
	v_addc_co_u32_e32 v5, vcc, 0, v3, vcc
	flat_store_dword v[4:5], v7
	ds_read_b32 v4, v47 offset:41984
	ds_read_b32 v5, v47 offset:43264
	v_add_co_u32_e32 v2, vcc, 0x18000, v2
	s_waitcnt lgkmcnt(0)
	v_add_f32_e32 v4, v4, v5
	ds_read_b32 v5, v47 offset:44544
	v_addc_co_u32_e32 v3, vcc, 0, v3, vcc
	s_waitcnt lgkmcnt(0)
	v_add_f32_e32 v4, v4, v5
	ds_read_b32 v5, v47 offset:45824
	s_waitcnt lgkmcnt(0)
	v_add_f32_e32 v4, v4, v5
	v_add_f32_e32 v4, v6, v4
	flat_store_dword v[2:3], v4
	s_branch .LBB0_2

; DI int opaque_tid() { int t = threadIdx.x; asm volatile("" : "+v"(t)); return t; }
; DI void phase_final(const Params& p) {
;     ...
;   const int tid_ = opaque_tid(), lane = tid_ & 63, gw = blockIdx.x * 4 + (tid_ >> 6), nw = gridDim.x * 4;
;   const float* X = (const float*)(WS_ + O_X);
;   for (int r = gw; r < NB * SEQ; r += nw) {
;     const int b = r >> 12, t = r & 4095;
;     const f32x4* xr = (const f32x4*)(X + ((size_t)b * SP + CTX + t) * DM);
;     f32x4 v[8]; float ss = 0.f;
; #pragma unroll
;     for (int j = 0; j < 8; ++j) { v[j] = xr[lane + 64 * j]; ss += v[j][0] * v[j][0] + v[j][1] * v[j][1] + v[j][2] * v[j][2] + v[j][3] * v[j][3]; }
; #pragma unroll
;     for (int o = 1; o < 64; o <<= 1) ss += __shfl_xor(ss, o);
;     const float rs = rsqrtf(ss * (1.f / DM) + EPS);
;     f32x4* dst = (f32x4*)(p.out + (size_t)r * DM);
; #pragma unroll
;     for (int j = 0; j < 8; ++j) {
;       const f32x4 g = *(const f32x4*)(p.final_g + 4 * (lane + 64 * j));
.LBB0_605:
	v_readlane_b32 s0, v255, 5
	v_ashrrev_i32_e32 v0, 6, v216
	s_nop 0
	v_add_u32_e32 v0, s0, v0
	s_movk_i32 s0, 0x4000
	v_cmp_gt_i32_e32 vcc, s0, v0
	s_and_saveexec_b64 s[0:1], vcc
	s_cbranch_execz .LBB0_608
	v_xor_b32_e32 v1, 1, v220
	v_cmp_lt_i32_e32 vcc, v1, v221
	v_and_b32_e32 v22, 63, v216
	v_mov_b32_e32 v3, 0
	v_cndmask_b32_e32 v1, v220, v1, vcc
	v_lshlrev_b32_e32 v32, 2, v1
	v_xor_b32_e32 v1, 2, v220
	v_cmp_lt_i32_e32 vcc, v1, v221
	v_or_b32_e32 v24, 0x100, v22
	v_or_b32_e32 v26, 0x140, v22
	v_cndmask_b32_e32 v1, v220, v1, vcc
	v_lshlrev_b32_e32 v33, 2, v1
	v_xor_b32_e32 v1, 4, v220
	v_cmp_lt_i32_e32 vcc, v1, v221
	v_or_b32_e32 v28, 0x180, v22
	v_or_b32_e32 v30, 0x1c0, v22
	v_cndmask_b32_e32 v1, v220, v1, vcc
	v_lshlrev_b32_e32 v34, 2, v1
	v_xor_b32_e32 v1, 8, v220
	v_cmp_lt_i32_e32 vcc, v1, v221
	v_lshlrev_b32_e32 v2, 4, v22
	v_readlane_b32 s0, v254, 16
	v_cndmask_b32_e32 v1, v220, v1, vcc
	v_lshlrev_b32_e32 v35, 2, v1
	v_xor_b32_e32 v1, 16, v220
	v_cmp_lt_i32_e32 vcc, v1, v221
	v_readlane_b32 s1, v254, 17
	v_readlane_b32 s2, v254, 18
	v_cndmask_b32_e32 v1, v220, v1, vcc
	v_cmp_lt_i32_e32 vcc, v222, v221
	v_lshlrev_b32_e32 v36, 2, v1
	v_readlane_b32 s3, v254, 19
	v_cndmask_b32_e32 v1, v220, v222, vcc
	v_lshlrev_b32_e32 v37, 2, v1
	v_ashrrev_i32_e32 v1, 31, v0
	v_lshlrev_b64 v[20:21], 13, v[0:1]
	v_or_b32_e32 v6, 0x400, v2
	v_mov_b32_e32 v7, v3
	v_or_b32_e32 v8, 0x800, v2
	v_mov_b32_e32 v9, v3
	v_or_b32_e32 v10, 0xc00, v2
	v_mov_b32_e32 v11, v3
	v_lshlrev_b32_e32 v12, 4, v24
	v_mov_b32_e32 v13, v3
	v_lshlrev_b32_e32 v14, 4, v26
	v_mov_b32_e32 v15, v3
	v_lshlrev_b32_e32 v16, 4, v28
	v_mov_b32_e32 v17, v3
	v_lshlrev_b32_e32 v18, 4, v30
	v_mov_b32_e32 v19, v3
	v_or_b32_e32 v20, v20, v2
	v_lshl_add_u64 v[4:5], s[0:1], 0, v[2:3]
	v_lshl_add_u64 v[6:7], s[0:1], 0, v[6:7]
	v_lshl_add_u64 v[8:9], s[0:1], 0, v[8:9]
	v_lshl_add_u64 v[10:11], s[0:1], 0, v[10:11]
	v_lshl_add_u64 v[12:13], s[0:1], 0, v[12:13]
	v_lshl_add_u64 v[14:15], s[0:1], 0, v[14:15]
	v_lshl_add_u64 v[16:17], s[0:1], 0, v[16:17]
	v_lshl_add_u64 v[18:19], s[0:1], 0, v[18:19]
	v_lshl_add_u64 v[20:21], s[2:3], 0, v[20:21]
	s_mov_b64 s[0:1], 0x1000
	v_lshl_add_u64 v[20:21], v[20:21], 0, s[0:1]
	s_mov_b64 s[0:1], 0
	v_lshlrev_b32_e32 v22, 4, v22
	v_mov_b32_e32 v23, v3
	v_lshlrev_b32_e32 v24, 4, v24
	v_mov_b32_e32 v25, v3
	v_lshlrev_b32_e32 v26, 4, v26
	v_mov_b32_e32 v27, v3
	v_lshlrev_b32_e32 v28, 4, v28
	v_mov_b32_e32 v29, v3
	v_lshlrev_b32_e32 v30, 4, v30
	v_mov_b32_e32 v31, v3
	v_mov_b32_e32 v1, 0x358637bd
	s_mov_b32 s2, 0x800000
	s_movk_i32 s3, 0x3fff
	global_load_dwordx4 v[150:153], v[4:5], off
	global_load_dwordx4 v[154:157], v[6:7], off
	global_load_dwordx4 v[158:161], v[8:9], off
	global_load_dwordx4 v[162:165], v[10:11], off
	global_load_dwordx4 v[166:169], v[12:13], off
	global_load_dwordx4 v[170:173], v[14:15], off
	global_load_dwordx4 v[174:177], v[16:17], off
	global_load_dwordx4 v[178:181], v[18:19], off
	s_waitcnt vmcnt(0)
; DI void phase_final(const Params& p) {
;     ...
;   for (int r = gw; r < NB * SEQ; r += nw) {
;     const int b = r >> 12, t = r & 4095;
;     const f32x4* xr = (const f32x4*)(X + ((size_t)b * SP + CTX + t) * DM);
;     f32x4 v[8]; float ss = 0.f;
; #pragma unroll
;     for (int j = 0; j < 8; ++j) { v[j] = xr[lane + 64 * j]; ss += v[j][0] * v[j][0] + v[j][1] * v[j][1] + v[j][2] * v[j][2] + v[j][3] * v[j][3]; }
; #pragma unroll
;     for (int o = 1; o < 64; o <<= 1) ss += __shfl_xor(ss, o);
;     const float rs = rsqrtf(ss * (1.f / DM) + EPS);
;     f32x4* dst = (f32x4*)(p.out + (size_t)r * DM);
; #pragma unroll
;     for (int j = 0; j < 8; ++j) {
;       const f32x4 g = *(const f32x4*)(p.final_g + 4 * (lane + 64 * j));
;       f32x4 o; for (int q = 0; q < 4; ++q) o[q] = v[j][q] * rs * g[q];
;       dst[lane + 64 * j] = o;
;     }
.LBB0_607:
	v_ashrrev_i32_e32 v2, 12, v0
	v_and_b32_e32 v40, 0xfff, v0
	v_mul_hi_i32_i24_e32 v39, 0x1100, v2
	v_mul_i32_i24_e32 v38, 0x1100, v2
	v_add_u32_e32 v2, 0x100, v40
	v_lshl_add_u64 v[38:39], v[38:39], 0, v[2:3]
	v_lshlrev_b64 v[38:39], 13, v[38:39]
	v_lshl_add_u64 v[38:39], s[84:85], 0, v[38:39]
	v_lshl_add_u64 v[74:75], v[38:39], 0, v[22:23]
	v_lshl_add_u64 v[76:77], v[38:39], 0, v[24:25]
	v_lshl_add_u64 v[78:79], v[38:39], 0, v[26:27]
	v_lshl_add_u64 v[80:81], v[38:39], 0, v[28:29]
	v_lshl_add_u64 v[82:83], v[38:39], 0, v[30:31]
	flat_load_dwordx4 v[38:41], v[74:75]
	flat_load_dwordx4 v[42:45], v[74:75] offset:1024
	flat_load_dwordx4 v[46:49], v[74:75] offset:2048
	flat_load_dwordx4 v[50:53], v[74:75] offset:3072
	flat_load_dwordx4 v[54:57], v[76:77]
	flat_load_dwordx4 v[58:61], v[78:79]
	flat_load_dwordx4 v[62:65], v[80:81]
	flat_load_dwordx4 v[66:69], v[82:83]
	v_mov_b32_e32 v70, v150
	v_mov_b32_e32 v71, v151
	v_mov_b32_e32 v72, v152
	v_mov_b32_e32 v73, v153
	v_add_u32_e32 v0, s94, v0
	s_waitcnt vmcnt(0) lgkmcnt(0)
	v_mul_f32_e32 v2, v39, v39
	v_mul_f32_e32 v90, v43, v43
	v_mul_f32_e32 v91, v47, v47
	v_fmac_f32_e32 v2, v38, v38
	v_fmac_f32_e32 v90, v42, v42
	v_mul_f32_e32 v92, v51, v51
	v_mov_b32_e32 v76, v55
	v_mov_b32_e32 v77, v59
	v_fmac_f32_e32 v91, v46, v46
	v_fmac_f32_e32 v2, v40, v40
	v_fmac_f32_e32 v90, v44, v44
	v_mov_b32_e32 v74, v54
	v_mov_b32_e32 v75, v58
	v_fmac_f32_e32 v92, v50, v50
	v_pk_mul_f32 v[76:77], v[76:77], v[76:77]
	v_fmac_f32_e32 v91, v48, v48
	v_fmac_f32_e32 v2, v41, v41
	v_fmac_f32_e32 v90, v45, v45
	v_mov_b32_e32 v78, v56
	v_mov_b32_e32 v79, v60
	v_mov_b32_e32 v84, v63
	v_mov_b32_e32 v85, v67
	v_fmac_f32_e32 v92, v52, v52
	v_pk_fma_f32 v[74:75], v[74:75], v[74:75], v[76:77]
	v_fmac_f32_e32 v91, v49, v49
	v_add_f32_e32 v2, v2, v90
	v_mov_b32_e32 v80, v57
	v_mov_b32_e32 v81, v61
	v_mov_b32_e32 v82, v62
	v_mov_b32_e32 v83, v66
	v_pk_mul_f32 v[84:85], v[84:85], v[84:85]
	v_fmac_f32_e32 v92, v53, v53
	v_pk_fma_f32 v[74:75], v[78:79], v[78:79], v[74:75]
	v_add_f32_e32 v2, v2, v91
	v_mov_b32_e32 v86, v64
	v_mov_b32_e32 v87, v68
	v_pk_fma_f32 v[76:77], v[82:83], v[82:83], v[84:85]
	v_pk_fma_f32 v[74:75], v[80:81], v[80:81], v[74:75]
	v_add_f32_e32 v2, v2, v92
	v_mov_b32_e32 v88, v65
	v_mov_b32_e32 v89, v69
	v_pk_fma_f32 v[76:77], v[86:87], v[86:87], v[76:77]
	v_add_f32_e32 v2, v2, v74
	v_pk_fma_f32 v[76:77], v[88:89], v[88:89], v[76:77]
	v_add_f32_e32 v2, v2, v75
	v_add_f32_e32 v2, v2, v76
	v_add_f32_e32 v2, v2, v77
	ds_bpermute_b32 v74, v32, v2
	s_waitcnt lgkmcnt(0)
	v_add_f32_e32 v2, v2, v74
	ds_bpermute_b32 v74, v33, v2
	s_waitcnt lgkmcnt(0)
	v_add_f32_e32 v2, v2, v74
	ds_bpermute_b32 v74, v34, v2
	s_waitcnt lgkmcnt(0)
	v_add_f32_e32 v2, v2, v74
	ds_bpermute_b32 v74, v35, v2
	s_waitcnt lgkmcnt(0)
	v_add_f32_e32 v2, v2, v74
	ds_bpermute_b32 v74, v36, v2
	s_waitcnt lgkmcnt(0)
	v_add_f32_e32 v2, v2, v74
	ds_bpermute_b32 v74, v37, v2
	s_waitcnt lgkmcnt(0)
	v_add_f32_e32 v2, v2, v74
	v_fmamk_f32 v2, v2, 0x3a000000, v1
	v_mul_f32_e32 v74, 0x4b800000, v2
	v_cmp_gt_f32_e32 vcc, s2, v2
	s_nop 1
	v_cndmask_b32_e32 v2, v2, v74, vcc
	v_rsq_f32_e32 v2, v2
	s_nop 0
	v_mul_f32_e32 v74, 0x45800000, v2
	v_cndmask_b32_e32 v2, v2, v74, vcc
	v_pk_mul_f32 v[38:39], v[38:39], v[2:3] op_sel_hi:[1,0]
	v_pk_mul_f32 v[40:41], v[40:41], v[2:3] op_sel_hi:[1,0]
	v_pk_mul_f32 v[38:39], v[70:71], v[38:39]
	v_pk_mul_f32 v[40:41], v[72:73], v[40:41]
	global_store_dwordx4 v[20:21], v[38:41], off offset:-4096
	s_nop 1
	v_mov_b32_e32 v38, v154
	v_mov_b32_e32 v39, v155
	v_mov_b32_e32 v40, v156
	v_mov_b32_e32 v41, v157
	v_pk_mul_f32 v[44:45], v[44:45], v[2:3] op_sel_hi:[1,0]
	v_pk_mul_f32 v[42:43], v[42:43], v[2:3] op_sel_hi:[1,0]
	v_cmp_lt_i32_e32 vcc, s3, v0
	s_or_b64 s[0:1], vcc, s[0:1]
	v_pk_mul_f32 v[38:39], v[38:39], v[42:43]
	v_pk_mul_f32 v[40:41], v[40:41], v[44:45]
	global_store_dwordx4 v[20:21], v[38:41], off offset:-3072
	s_nop 1
	v_mov_b32_e32 v38, v158
	v_mov_b32_e32 v39, v159
	v_mov_b32_e32 v40, v160
	v_mov_b32_e32 v41, v161
	v_pk_mul_f32 v[42:43], v[48:49], v[2:3] op_sel_hi:[1,0]
	v_pk_mul_f32 v[44:45], v[46:47], v[2:3] op_sel_hi:[1,0]
	v_pk_mul_f32 v[40:41], v[40:41], v[42:43]
	v_pk_mul_f32 v[38:39], v[38:39], v[44:45]
	global_store_dwordx4 v[20:21], v[38:41], off offset:-2048
	s_nop 1
	v_mov_b32_e32 v38, v162
	v_mov_b32_e32 v39, v163
	v_mov_b32_e32 v40, v164
	v_mov_b32_e32 v41, v165
	v_pk_mul_f32 v[42:43], v[52:53], v[2:3] op_sel_hi:[1,0]
	v_pk_mul_f32 v[44:45], v[50:51], v[2:3] op_sel_hi:[1,0]
	v_pk_mul_f32 v[40:41], v[40:41], v[42:43]
	v_pk_mul_f32 v[38:39], v[38:39], v[44:45]
	global_store_dwordx4 v[20:21], v[38:41], off offset:-1024
	s_nop 1
	v_mov_b32_e32 v38, v166
	v_mov_b32_e32 v39, v167
	v_mov_b32_e32 v40, v168
	v_mov_b32_e32 v41, v169
	v_pk_mul_f32 v[42:43], v[56:57], v[2:3] op_sel_hi:[1,0]
	v_pk_mul_f32 v[44:45], v[54:55], v[2:3] op_sel_hi:[1,0]
	v_pk_mul_f32 v[40:41], v[40:41], v[42:43]
	v_pk_mul_f32 v[38:39], v[38:39], v[44:45]
	global_store_dwordx4 v[20:21], v[38:41], off
	s_nop 1
	v_mov_b32_e32 v38, v170
	v_mov_b32_e32 v39, v171
	v_mov_b32_e32 v40, v172
	v_mov_b32_e32 v41, v173
	v_pk_mul_f32 v[42:43], v[60:61], v[2:3] op_sel_hi:[1,0]
	v_pk_mul_f32 v[44:45], v[58:59], v[2:3] op_sel_hi:[1,0]
	v_pk_mul_f32 v[40:41], v[40:41], v[42:43]
	v_pk_mul_f32 v[38:39], v[38:39], v[44:45]
	global_store_dwordx4 v[20:21], v[38:41], off offset:1024
	s_nop 1
	v_mov_b32_e32 v38, v174
	v_mov_b32_e32 v39, v175
	v_mov_b32_e32 v40, v176
	v_mov_b32_e32 v41, v177
	v_pk_mul_f32 v[42:43], v[64:65], v[2:3] op_sel_hi:[1,0]
	v_pk_mul_f32 v[44:45], v[62:63], v[2:3] op_sel_hi:[1,0]
	v_pk_mul_f32 v[40:41], v[40:41], v[42:43]
	v_pk_mul_f32 v[38:39], v[38:39], v[44:45]
	global_store_dwordx4 v[20:21], v[38:41], off offset:2048
	s_nop 1
	v_mov_b32_e32 v38, v178
	v_mov_b32_e32 v39, v179
	v_mov_b32_e32 v40, v180
	v_mov_b32_e32 v41, v181
	v_pk_mul_f32 v[42:43], v[68:69], v[2:3] op_sel_hi:[1,0]
	v_pk_mul_f32 v[44:45], v[66:67], v[2:3] op_sel_hi:[1,0]
	v_pk_mul_f32 v[40:41], v[42:43], v[40:41]
	v_pk_mul_f32 v[38:39], v[44:45], v[38:39]
	global_store_dwordx4 v[20:21], v[38:41], off offset:3072
	v_lshl_add_u64 v[20:21], v[20:21], 0, s[60:61]
	s_andn2_b64 exec, exec, s[0:1]
	s_cbranch_execnz .LBB0_607
